# NA neighbourhood-attention bias lookup batched: 32 serialized exec-masked ds_read_b32+wait blocks replaced by 16 ds_read2_b32 + cndmask (3 of 4 copies)
# speedup vs baseline: 1.0069x; 1.0069x over previous
.LBB0_232:
	s_add_i32 s6, s1, -2
	s_cmp_lt_u32 s6, 4
	s_cbranch_scc1 .LBB0_298
	s_add_i32 s6, s18, -6
	s_and_b32 s10, s6, 0x7ffffffc
	s_sub_i32 s6, s19, 48
	v_and_or_b32 v195, s6, 16, v148
	s_add_i32 s10, s10, s17
	v_add_u32_e32 v195, s8, v195
	v_sub_u32_e32 v160, v195, v166
	v_sub_u32_e32 v194, s10, v151
	v_lshlrev_b32_e32 v160, 2, v160
	v_mad_i32_i24 v160, v194, s5, v160
	v_add_u32_e32 v160, 0x163a0, v160
	ds_read2_b32 v[80:81], v160 offset0:0 offset1:1
	ds_read2_b32 v[82:83], v160 offset0:2 offset1:3
	ds_read2_b32 v[84:85], v160 offset0:8 offset1:9
	ds_read2_b32 v[86:87], v160 offset0:10 offset1:11
	ds_read2_b32 v[88:89], v160 offset0:31 offset1:32
	ds_read2_b32 v[90:91], v160 offset0:33 offset1:34
	ds_read2_b32 v[92:93], v160 offset0:39 offset1:40
	ds_read2_b32 v[94:95], v160 offset0:41 offset1:42
	ds_read2_b32 v[64:65], v160 offset0:62 offset1:63
	ds_read2_b32 v[66:67], v160 offset0:64 offset1:65
	ds_read2_b32 v[68:69], v160 offset0:70 offset1:71
	ds_read2_b32 v[70:71], v160 offset0:72 offset1:73
	ds_read2_b32 v[72:73], v160 offset0:93 offset1:94
	ds_read2_b32 v[74:75], v160 offset0:95 offset1:96
	ds_read2_b32 v[76:77], v160 offset0:101 offset1:102
	ds_read2_b32 v[78:79], v160 offset0:103 offset1:104
	v_sub_u32_e32 v195, v195, v170
	v_sub_u32_e32 v194, s10, v169
	v_cmp_gt_u32_e64 s[38:39], 16, v195
	v_add_u32_e32 v195, 1, v195
	v_cmp_gt_u32_e64 s[40:41], 16, v195
	v_add_u32_e32 v195, 1, v195
	v_cmp_gt_u32_e64 s[42:43], 16, v195
	v_add_u32_e32 v195, 1, v195
	v_cmp_gt_u32_e64 s[44:45], 16, v195
	v_add_u32_e32 v195, 5, v195
	v_cmp_gt_u32_e64 s[46:47], 16, v195
	v_add_u32_e32 v195, 1, v195
	v_cmp_gt_u32_e64 s[48:49], 16, v195
	v_add_u32_e32 v195, 1, v195
	v_cmp_gt_u32_e64 s[50:51], 16, v195
	v_add_u32_e32 v195, 1, v195
	v_cmp_gt_u32_e64 s[52:53], 16, v195
	v_cmp_gt_u32_e64 s[54:55], 8, v194
	v_add_u32_e32 v194, 1, v194
	v_cmp_gt_u32_e64 s[24:25], 8, v194
	v_add_u32_e32 v194, 1, v194
	v_cmp_gt_u32_e64 s[6:7], 8, v194
	v_add_u32_e32 v194, 1, v194
	v_cmp_gt_u32_e64 s[10:11], 8, v194
	s_waitcnt lgkmcnt(0)
	v_add_f32_e32 v80, v48, v80
	v_add_f32_e32 v81, v49, v81
	v_add_f32_e32 v82, v50, v82
	v_add_f32_e32 v83, v51, v83
	v_add_f32_e32 v84, v52, v84
	v_add_f32_e32 v85, v53, v85
	v_add_f32_e32 v86, v54, v86
	v_add_f32_e32 v87, v55, v87
	v_add_f32_e32 v88, v56, v88
	v_add_f32_e32 v89, v57, v89
	v_add_f32_e32 v90, v58, v90
	v_add_f32_e32 v91, v59, v91
	v_add_f32_e32 v92, v60, v92
	v_add_f32_e32 v93, v61, v93
	v_add_f32_e32 v94, v62, v94
	v_add_f32_e32 v95, v63, v95
	s_and_b64 vcc, s[38:39], s[54:55]
	v_cndmask_b32_e32 v48, v233, v80, vcc
	s_and_b64 vcc, s[40:41], s[54:55]
	v_cndmask_b32_e32 v49, v233, v81, vcc
	s_and_b64 vcc, s[42:43], s[54:55]
	v_cndmask_b32_e32 v50, v233, v82, vcc
	s_and_b64 vcc, s[44:45], s[54:55]
	v_cndmask_b32_e32 v51, v233, v83, vcc
	s_and_b64 vcc, s[46:47], s[54:55]
	v_cndmask_b32_e32 v52, v233, v84, vcc
	s_and_b64 vcc, s[48:49], s[54:55]
	v_cndmask_b32_e32 v53, v233, v85, vcc
	s_and_b64 vcc, s[50:51], s[54:55]
	v_cndmask_b32_e32 v54, v233, v86, vcc
	s_and_b64 vcc, s[52:53], s[54:55]
	v_cndmask_b32_e32 v55, v233, v87, vcc
	s_and_b64 vcc, s[38:39], s[24:25]
	v_cndmask_b32_e32 v56, v233, v88, vcc
	s_and_b64 vcc, s[40:41], s[24:25]
	v_cndmask_b32_e32 v57, v233, v89, vcc
	s_and_b64 vcc, s[42:43], s[24:25]
	v_cndmask_b32_e32 v58, v233, v90, vcc
	s_and_b64 vcc, s[44:45], s[24:25]
	v_cndmask_b32_e32 v59, v233, v91, vcc
	s_and_b64 vcc, s[46:47], s[24:25]
	v_cndmask_b32_e32 v60, v233, v92, vcc
	s_and_b64 vcc, s[48:49], s[24:25]
	v_cndmask_b32_e32 v61, v233, v93, vcc
	s_and_b64 vcc, s[50:51], s[24:25]
	v_cndmask_b32_e32 v62, v233, v94, vcc
	s_and_b64 vcc, s[52:53], s[24:25]
	v_cndmask_b32_e32 v63, v233, v95, vcc
	v_add_f32_e32 v64, v32, v64
	v_add_f32_e32 v65, v33, v65
	v_add_f32_e32 v66, v34, v66
	v_add_f32_e32 v67, v35, v67
	v_add_f32_e32 v68, v36, v68
	v_add_f32_e32 v69, v37, v69
	v_add_f32_e32 v70, v38, v70
	v_add_f32_e32 v71, v39, v71
	v_add_f32_e32 v72, v40, v72
	v_add_f32_e32 v73, v41, v73
	v_add_f32_e32 v74, v42, v74
	v_add_f32_e32 v75, v43, v75
	v_add_f32_e32 v76, v44, v76
	v_add_f32_e32 v77, v45, v77
	v_add_f32_e32 v78, v46, v78
	v_add_f32_e32 v79, v47, v79
	s_and_b64 vcc, s[38:39], s[6:7]
	v_cndmask_b32_e32 v32, v233, v64, vcc
	s_and_b64 vcc, s[40:41], s[6:7]
	v_cndmask_b32_e32 v33, v233, v65, vcc
	s_and_b64 vcc, s[42:43], s[6:7]
	v_cndmask_b32_e32 v34, v233, v66, vcc
	s_and_b64 vcc, s[44:45], s[6:7]
	v_cndmask_b32_e32 v35, v233, v67, vcc
	s_and_b64 vcc, s[46:47], s[6:7]
	v_cndmask_b32_e32 v36, v233, v68, vcc
	s_and_b64 vcc, s[48:49], s[6:7]
	v_cndmask_b32_e32 v37, v233, v69, vcc
	s_and_b64 vcc, s[50:51], s[6:7]
	v_cndmask_b32_e32 v38, v233, v70, vcc
	s_and_b64 vcc, s[52:53], s[6:7]
	v_cndmask_b32_e32 v39, v233, v71, vcc
	s_and_b64 vcc, s[38:39], s[10:11]
	v_cndmask_b32_e32 v40, v233, v72, vcc
	s_and_b64 vcc, s[40:41], s[10:11]
	v_cndmask_b32_e32 v41, v233, v73, vcc
	s_and_b64 vcc, s[42:43], s[10:11]
	v_cndmask_b32_e32 v42, v233, v74, vcc
	s_and_b64 vcc, s[44:45], s[10:11]
	v_cndmask_b32_e32 v43, v233, v75, vcc
	s_and_b64 vcc, s[46:47], s[10:11]
	v_cndmask_b32_e32 v44, v233, v76, vcc
	s_and_b64 vcc, s[48:49], s[10:11]
	v_cndmask_b32_e32 v45, v233, v77, vcc
	s_and_b64 vcc, s[50:51], s[10:11]
	v_cndmask_b32_e32 v46, v233, v78, vcc
	s_and_b64 vcc, s[52:53], s[10:11]
	v_cndmask_b32_e32 v47, v233, v79, vcc

.LBB0_302:
	s_add_i32 s1, s1, -2
	s_cmp_lt_u32 s1, 4
	s_cbranch_scc1 .LBB0_368
	s_lshl_b32 s6, s1, 1
	s_and_b32 s10, s6, 0x7ffffffc
	s_lshl_b32 s6, s1, 4
	v_and_or_b32 v195, s6, 16, v148
	s_add_i32 s10, s10, s17
	v_add_u32_e32 v195, s8, v195
	v_sub_u32_e32 v160, v195, v166
	v_sub_u32_e32 v194, s10, v151
	v_lshlrev_b32_e32 v160, 2, v160
	v_mad_i32_i24 v160, v194, s5, v160
	v_add_u32_e32 v160, 0x163a0, v160
	ds_read2_b32 v[82:83], v160 offset0:0 offset1:1
	ds_read2_b32 v[84:85], v160 offset0:2 offset1:3
	ds_read2_b32 v[86:87], v160 offset0:8 offset1:9
	ds_read2_b32 v[88:89], v160 offset0:10 offset1:11
	ds_read2_b32 v[90:91], v160 offset0:31 offset1:32
	ds_read2_b32 v[92:93], v160 offset0:33 offset1:34
	ds_read2_b32 v[94:95], v160 offset0:39 offset1:40
	ds_read2_b32 v[96:97], v160 offset0:41 offset1:42
	ds_read2_b32 v[66:67], v160 offset0:62 offset1:63
	ds_read2_b32 v[68:69], v160 offset0:64 offset1:65
	ds_read2_b32 v[70:71], v160 offset0:70 offset1:71
	ds_read2_b32 v[72:73], v160 offset0:72 offset1:73
	ds_read2_b32 v[74:75], v160 offset0:93 offset1:94
	ds_read2_b32 v[76:77], v160 offset0:95 offset1:96
	ds_read2_b32 v[78:79], v160 offset0:101 offset1:102
	ds_read2_b32 v[80:81], v160 offset0:103 offset1:104
	v_sub_u32_e32 v195, v195, v170
	v_sub_u32_e32 v194, s10, v169
	v_cmp_gt_u32_e64 s[38:39], 16, v195
	v_add_u32_e32 v195, 1, v195
	v_cmp_gt_u32_e64 s[40:41], 16, v195
	v_add_u32_e32 v195, 1, v195
	v_cmp_gt_u32_e64 s[42:43], 16, v195
	v_add_u32_e32 v195, 1, v195
	v_cmp_gt_u32_e64 s[44:45], 16, v195
	v_add_u32_e32 v195, 5, v195
	v_cmp_gt_u32_e64 s[46:47], 16, v195
	v_add_u32_e32 v195, 1, v195
	v_cmp_gt_u32_e64 s[48:49], 16, v195
	v_add_u32_e32 v195, 1, v195
	v_cmp_gt_u32_e64 s[50:51], 16, v195
	v_add_u32_e32 v195, 1, v195
	v_cmp_gt_u32_e64 s[52:53], 16, v195
	v_cmp_gt_u32_e64 s[54:55], 8, v194
	v_add_u32_e32 v194, 1, v194
	v_cmp_gt_u32_e64 s[18:19], 8, v194
	v_add_u32_e32 v194, 1, v194
	v_cmp_gt_u32_e64 s[6:7], 8, v194
	v_add_u32_e32 v194, 1, v194
	v_cmp_gt_u32_e64 s[10:11], 8, v194
	s_waitcnt lgkmcnt(0)
	v_add_f32_e32 v82, v48, v82
	v_add_f32_e32 v83, v49, v83
	v_add_f32_e32 v84, v50, v84
	v_add_f32_e32 v85, v51, v85
	v_add_f32_e32 v86, v52, v86
	v_add_f32_e32 v87, v53, v87
	v_add_f32_e32 v88, v54, v88
	v_add_f32_e32 v89, v55, v89
	v_add_f32_e32 v90, v56, v90
	v_add_f32_e32 v91, v57, v91
	v_add_f32_e32 v92, v58, v92
	v_add_f32_e32 v93, v59, v93
	v_add_f32_e32 v94, v60, v94
	v_add_f32_e32 v95, v61, v95
	v_add_f32_e32 v96, v62, v96
	v_add_f32_e32 v97, v63, v97
	s_and_b64 vcc, s[38:39], s[54:55]
	v_cndmask_b32_e32 v48, v233, v82, vcc
	s_and_b64 vcc, s[40:41], s[54:55]
	v_cndmask_b32_e32 v49, v233, v83, vcc
	s_and_b64 vcc, s[42:43], s[54:55]
	v_cndmask_b32_e32 v50, v233, v84, vcc
	s_and_b64 vcc, s[44:45], s[54:55]
	v_cndmask_b32_e32 v51, v233, v85, vcc
	s_and_b64 vcc, s[46:47], s[54:55]
	v_cndmask_b32_e32 v52, v233, v86, vcc
	s_and_b64 vcc, s[48:49], s[54:55]
	v_cndmask_b32_e32 v53, v233, v87, vcc
	s_and_b64 vcc, s[50:51], s[54:55]
	v_cndmask_b32_e32 v54, v233, v88, vcc
	s_and_b64 vcc, s[52:53], s[54:55]
	v_cndmask_b32_e32 v55, v233, v89, vcc
	s_and_b64 vcc, s[38:39], s[18:19]
	v_cndmask_b32_e32 v56, v233, v90, vcc
	s_and_b64 vcc, s[40:41], s[18:19]
	v_cndmask_b32_e32 v57, v233, v91, vcc
	s_and_b64 vcc, s[42:43], s[18:19]
	v_cndmask_b32_e32 v58, v233, v92, vcc
	s_and_b64 vcc, s[44:45], s[18:19]
	v_cndmask_b32_e32 v59, v233, v93, vcc
	s_and_b64 vcc, s[46:47], s[18:19]
	v_cndmask_b32_e32 v60, v233, v94, vcc
	s_and_b64 vcc, s[48:49], s[18:19]
	v_cndmask_b32_e32 v61, v233, v95, vcc
	s_and_b64 vcc, s[50:51], s[18:19]
	v_cndmask_b32_e32 v62, v233, v96, vcc
	s_and_b64 vcc, s[52:53], s[18:19]
	v_cndmask_b32_e32 v63, v233, v97, vcc
	v_add_f32_e32 v66, v32, v66
	v_add_f32_e32 v67, v33, v67
	v_add_f32_e32 v68, v34, v68
	v_add_f32_e32 v69, v35, v69
	v_add_f32_e32 v70, v36, v70
	v_add_f32_e32 v71, v37, v71
	v_add_f32_e32 v72, v38, v72
	v_add_f32_e32 v73, v39, v73
	v_add_f32_e32 v74, v40, v74
	v_add_f32_e32 v75, v41, v75
	v_add_f32_e32 v76, v42, v76
	v_add_f32_e32 v77, v43, v77
	v_add_f32_e32 v78, v44, v78
	v_add_f32_e32 v79, v45, v79
	v_add_f32_e32 v80, v46, v80
	v_add_f32_e32 v81, v47, v81
	s_and_b64 vcc, s[38:39], s[6:7]
	v_cndmask_b32_e32 v32, v233, v66, vcc
	s_and_b64 vcc, s[40:41], s[6:7]
	v_cndmask_b32_e32 v33, v233, v67, vcc
	s_and_b64 vcc, s[42:43], s[6:7]
	v_cndmask_b32_e32 v34, v233, v68, vcc
	s_and_b64 vcc, s[44:45], s[6:7]
	v_cndmask_b32_e32 v35, v233, v69, vcc
	s_and_b64 vcc, s[46:47], s[6:7]
	v_cndmask_b32_e32 v36, v233, v70, vcc
	s_and_b64 vcc, s[48:49], s[6:7]
	v_cndmask_b32_e32 v37, v233, v71, vcc
	s_and_b64 vcc, s[50:51], s[6:7]
	v_cndmask_b32_e32 v38, v233, v72, vcc
	s_and_b64 vcc, s[52:53], s[6:7]
	v_cndmask_b32_e32 v39, v233, v73, vcc
	s_and_b64 vcc, s[38:39], s[10:11]
	v_cndmask_b32_e32 v40, v233, v74, vcc
	s_and_b64 vcc, s[40:41], s[10:11]
	v_cndmask_b32_e32 v41, v233, v75, vcc
	s_and_b64 vcc, s[42:43], s[10:11]
	v_cndmask_b32_e32 v42, v233, v76, vcc
	s_and_b64 vcc, s[44:45], s[10:11]
	v_cndmask_b32_e32 v43, v233, v77, vcc
	s_and_b64 vcc, s[46:47], s[10:11]
	v_cndmask_b32_e32 v44, v233, v78, vcc
	s_and_b64 vcc, s[48:49], s[10:11]
	v_cndmask_b32_e32 v45, v233, v79, vcc
	s_and_b64 vcc, s[50:51], s[10:11]
	v_cndmask_b32_e32 v46, v233, v80, vcc
	s_and_b64 vcc, s[52:53], s[10:11]
	v_cndmask_b32_e32 v47, v233, v81, vcc

.LBB0_446:
	s_add_i32 s11, s16, -1
	s_and_b32 s12, s11, 1
	s_mul_i32 s0, s12, 0x3400
	v_add_u32_e32 v48, s0, v171
	ds_read_b128 v[126:129], v48
	ds_read_b128 v[134:137], v48 offset:32
	ds_read_b128 v[138:141], v48 offset:4608
	ds_read_b128 v[142:145], v48 offset:4640
	s_and_b32 s17, s16, 1
	v_xor_b32_e32 v50, 0x80000000, v161
	s_mul_i32 s0, s17, 0x2400
	v_mov_b32_e32 v51, v50
	v_mov_b32_e32 v52, v50
	v_mov_b32_e32 v53, v50
	v_mov_b32_e32 v54, v50
	v_mov_b32_e32 v55, v50
	v_mov_b32_e32 v56, v50
	v_mov_b32_e32 v57, v50
	v_mov_b32_e32 v58, v50
	v_mov_b32_e32 v59, v50
	v_mov_b32_e32 v60, v50
	v_mov_b32_e32 v61, v50
	v_mov_b32_e32 v62, v50
	v_mov_b32_e32 v63, v50
	v_mov_b32_e32 v64, v50
	v_mov_b32_e32 v65, v50
	v_add_u32_e32 v49, s0, v153
	s_waitcnt lgkmcnt(3)
	v_mfma_f32_32x32x16_bf16 v[66:81], v[126:129], v[100:103], v[50:65]
	s_waitcnt lgkmcnt(1)
	v_mfma_f32_32x32x16_bf16 v[50:65], v[138:141], v[100:103], v[50:65]
	ds_read_b128 v[126:129], v48 offset:64
	ds_read_b128 v[138:141], v48 offset:4672
	v_mfma_f32_32x32x16_bf16 v[66:81], v[134:137], v[104:107], v[66:81]
	s_waitcnt lgkmcnt(2)
	v_mfma_f32_32x32x16_bf16 v[50:65], v[142:145], v[104:107], v[50:65]
	ds_read_b128 v[134:137], v48 offset:96
	ds_read_b128 v[142:145], v48 offset:4704
	s_waitcnt lgkmcnt(3)
	v_mfma_f32_32x32x16_bf16 v[66:81], v[126:129], v[108:111], v[66:81]
	s_waitcnt lgkmcnt(2)
	v_mfma_f32_32x32x16_bf16 v[50:65], v[138:141], v[108:111], v[50:65]
	ds_read_b64_tr_b16 v[126:127], v49 offset:26624
	ds_read_b64_tr_b16 v[128:129], v49 offset:27776
	ds_read_b64_tr_b16 v[140:141], v49 offset:27840
	ds_read_b64_tr_b16 v[138:139], v49 offset:26688
	s_waitcnt lgkmcnt(5)
	v_mfma_f32_32x32x16_bf16 v[66:81], v[134:137], v[112:115], v[66:81]
	s_waitcnt lgkmcnt(4)
	v_mfma_f32_32x32x16_bf16 v[50:65], v[142:145], v[112:115], v[50:65]
	ds_read_b64_tr_b16 v[134:135], v49 offset:28928
	ds_read_b64_tr_b16 v[136:137], v49 offset:30080
	ds_read_b64_tr_b16 v[144:145], v49 offset:30144
	ds_read_b64_tr_b16 v[142:143], v49 offset:28992
	s_waitcnt lgkmcnt(6)
	v_mfma_f32_32x32x16_bf16 v[16:31], v[126:129], v[44:47], v[16:31]
	s_waitcnt lgkmcnt(4)
	v_mfma_f32_32x32x16_bf16 v[0:15], v[138:141], v[44:47], v[0:15]
	ds_read_b64_tr_b16 v[44:45], v49 offset:31232
	ds_read_b64_tr_b16 v[46:47], v49 offset:32384
	ds_read_b64_tr_b16 v[128:129], v49 offset:32448
	ds_read_b64_tr_b16 v[126:127], v49 offset:31296
	s_waitcnt lgkmcnt(6)
	v_mfma_f32_32x32x16_bf16 v[16:31], v[134:137], v[40:43], v[16:31]
	s_waitcnt lgkmcnt(4)
	v_mfma_f32_32x32x16_bf16 v[0:15], v[142:145], v[40:43], v[0:15]
	ds_read_b64_tr_b16 v[40:41], v49 offset:33536
	ds_read_b64_tr_b16 v[42:43], v49 offset:34688
	ds_read_b64_tr_b16 v[136:137], v49 offset:34752
	ds_read_b64_tr_b16 v[134:135], v49 offset:33600
	s_waitcnt lgkmcnt(6)
	v_mfma_f32_32x32x16_bf16 v[16:31], v[44:47], v[36:39], v[16:31]
	s_waitcnt lgkmcnt(4)
	v_mfma_f32_32x32x16_bf16 v[0:15], v[126:129], v[36:39], v[0:15]
	s_waitcnt lgkmcnt(2)
	v_mfma_f32_32x32x16_bf16 v[16:31], v[40:43], v[32:35], v[16:31]
	s_waitcnt lgkmcnt(0)
	v_mfma_f32_32x32x16_bf16 v[0:15], v[134:137], v[32:35], v[0:15]
	s_add_i32 s0, s6, -4
	s_and_b32 s10, s0, 28
	s_sub_i32 s0, s7, 32
	v_and_or_b32 v48, s0, 16, v148
	s_add_i32 s10, s10, s15
	v_add_u32_e32 v48, s8, v48
	v_sub_u32_e32 v98, v48, v166
	v_sub_u32_e32 v49, s10, v151
	v_lshlrev_b32_e32 v98, 2, v98
	v_mad_i32_i24 v98, v49, s5, v98
	v_add_u32_e32 v98, 0x163a0, v98
	ds_read2_b32 v[126:127], v98 offset0:62 offset1:63
	ds_read2_b32 v[128:129], v98 offset0:64 offset1:65
	ds_read2_b32 v[134:135], v98 offset0:70 offset1:71
	ds_read2_b32 v[136:137], v98 offset0:72 offset1:73
	ds_read2_b32 v[138:139], v98 offset0:93 offset1:94
	ds_read2_b32 v[140:141], v98 offset0:95 offset1:96
	ds_read2_b32 v[142:143], v98 offset0:101 offset1:102
	ds_read2_b32 v[144:145], v98 offset0:103 offset1:104
	v_sub_u32_e32 v48, v48, v170
	v_sub_u32_e32 v49, s10, v169
	v_cmp_gt_u32_e64 s[38:39], 16, v48
	v_add_u32_e32 v48, 1, v48
	v_cmp_gt_u32_e64 s[40:41], 16, v48
	v_add_u32_e32 v48, 1, v48
	v_cmp_gt_u32_e64 s[42:43], 16, v48
	v_add_u32_e32 v48, 1, v48
	v_cmp_gt_u32_e64 s[44:45], 16, v48
	v_add_u32_e32 v48, 5, v48
	v_cmp_gt_u32_e64 s[46:47], 16, v48
	v_add_u32_e32 v48, 1, v48
	v_cmp_gt_u32_e64 s[48:49], 16, v48
	v_add_u32_e32 v48, 1, v48
	v_cmp_gt_u32_e64 s[50:51], 16, v48
	v_add_u32_e32 v48, 1, v48
	v_cmp_gt_u32_e64 s[52:53], 16, v48
	v_add_u32_e32 v49, 2, v49
	v_cmp_gt_u32_e64 s[54:55], 8, v49
	v_add_u32_e32 v49, 1, v49
	v_cmp_gt_u32_e64 s[18:19], 8, v49
	s_waitcnt lgkmcnt(0)
	v_add_f32_e32 v126, v50, v126
	v_add_f32_e32 v127, v51, v127
	v_add_f32_e32 v128, v52, v128
	v_add_f32_e32 v129, v53, v129
	v_add_f32_e32 v134, v54, v134
	v_add_f32_e32 v135, v55, v135
	v_add_f32_e32 v136, v56, v136
	v_add_f32_e32 v137, v57, v137
	v_add_f32_e32 v138, v58, v138
	v_add_f32_e32 v139, v59, v139
	v_add_f32_e32 v140, v60, v140
	v_add_f32_e32 v141, v61, v141
	v_add_f32_e32 v142, v62, v142
	v_add_f32_e32 v143, v63, v143
	v_add_f32_e32 v144, v64, v144
	v_add_f32_e32 v145, v65, v145
	ds_read2_b32 v[50:51], v98 offset0:0 offset1:1
	ds_read2_b32 v[52:53], v98 offset0:2 offset1:3
	ds_read2_b32 v[54:55], v98 offset0:8 offset1:9
	ds_read2_b32 v[56:57], v98 offset0:10 offset1:11
	ds_read2_b32 v[58:59], v98 offset0:31 offset1:32
	ds_read2_b32 v[60:61], v98 offset0:33 offset1:34
	ds_read2_b32 v[62:63], v98 offset0:39 offset1:40
	ds_read2_b32 v[64:65], v98 offset0:41 offset1:42
	s_and_b64 vcc, s[38:39], s[54:55]
	v_cndmask_b32_e32 v32, v233, v126, vcc
	s_and_b64 vcc, s[40:41], s[54:55]
	v_cndmask_b32_e32 v33, v233, v127, vcc
	s_and_b64 vcc, s[42:43], s[54:55]
	v_cndmask_b32_e32 v34, v233, v128, vcc
	s_and_b64 vcc, s[44:45], s[54:55]
	v_cndmask_b32_e32 v35, v233, v129, vcc
	s_and_b64 vcc, s[46:47], s[54:55]
	v_cndmask_b32_e32 v36, v233, v134, vcc
	s_and_b64 vcc, s[48:49], s[54:55]
	v_cndmask_b32_e32 v37, v233, v135, vcc
	s_and_b64 vcc, s[50:51], s[54:55]
	v_cndmask_b32_e32 v38, v233, v136, vcc
	s_and_b64 vcc, s[52:53], s[54:55]
	v_cndmask_b32_e32 v39, v233, v137, vcc
	s_and_b64 vcc, s[38:39], s[18:19]
	v_cndmask_b32_e32 v40, v233, v138, vcc
	s_and_b64 vcc, s[40:41], s[18:19]
	v_cndmask_b32_e32 v41, v233, v139, vcc
	s_and_b64 vcc, s[42:43], s[18:19]
	v_cndmask_b32_e32 v42, v233, v140, vcc
	s_and_b64 vcc, s[44:45], s[18:19]
	v_cndmask_b32_e32 v43, v233, v141, vcc
	s_and_b64 vcc, s[46:47], s[18:19]
	v_cndmask_b32_e32 v44, v233, v142, vcc
	s_and_b64 vcc, s[48:49], s[18:19]
	v_cndmask_b32_e32 v45, v233, v143, vcc
	s_and_b64 vcc, s[50:51], s[18:19]
	v_cndmask_b32_e32 v46, v233, v144, vcc
	s_and_b64 vcc, s[52:53], s[18:19]
	v_cndmask_b32_e32 v47, v233, v145, vcc
	v_add_u32_e32 v49, -3, v49
	v_cmp_gt_u32_e64 s[54:55], 8, v49
	v_add_u32_e32 v49, 1, v49
	v_cmp_gt_u32_e64 s[18:19], 8, v49
	s_waitcnt lgkmcnt(0)
	v_add_f32_e32 v50, v66, v50
	v_add_f32_e32 v51, v67, v51
	v_add_f32_e32 v52, v68, v52
	v_add_f32_e32 v53, v69, v53
	v_add_f32_e32 v54, v70, v54
	v_add_f32_e32 v55, v71, v55
	v_add_f32_e32 v56, v72, v56
	v_add_f32_e32 v57, v73, v57
	v_add_f32_e32 v58, v74, v58
	v_add_f32_e32 v59, v75, v59
	v_add_f32_e32 v60, v76, v60
	v_add_f32_e32 v61, v77, v61
	v_add_f32_e32 v62, v78, v62
	v_add_f32_e32 v63, v79, v63
	v_add_f32_e32 v64, v80, v64
	v_add_f32_e32 v65, v81, v65
	s_and_b64 vcc, s[38:39], s[54:55]
	v_cndmask_b32_e32 v48, v233, v50, vcc
	s_and_b64 vcc, s[40:41], s[54:55]
	v_cndmask_b32_e32 v49, v233, v51, vcc
	s_and_b64 vcc, s[42:43], s[54:55]
	v_cndmask_b32_e32 v50, v233, v52, vcc
	s_and_b64 vcc, s[44:45], s[54:55]
	v_cndmask_b32_e32 v51, v233, v53, vcc
	s_and_b64 vcc, s[46:47], s[54:55]
	v_cndmask_b32_e32 v52, v233, v54, vcc
	s_and_b64 vcc, s[48:49], s[54:55]
	v_cndmask_b32_e32 v53, v233, v55, vcc
	s_and_b64 vcc, s[50:51], s[54:55]
	v_cndmask_b32_e32 v54, v233, v56, vcc
	s_and_b64 vcc, s[52:53], s[54:55]
	v_cndmask_b32_e32 v55, v233, v57, vcc
	s_and_b64 vcc, s[38:39], s[18:19]
	v_cndmask_b32_e32 v56, v233, v58, vcc
	s_and_b64 vcc, s[40:41], s[18:19]
	v_cndmask_b32_e32 v57, v233, v59, vcc
	s_and_b64 vcc, s[42:43], s[18:19]
	v_cndmask_b32_e32 v58, v233, v60, vcc
	s_and_b64 vcc, s[44:45], s[18:19]
	v_cndmask_b32_e32 v59, v233, v61, vcc
	s_and_b64 vcc, s[46:47], s[18:19]
	v_cndmask_b32_e32 v60, v233, v62, vcc
	s_and_b64 vcc, s[48:49], s[18:19]
	v_cndmask_b32_e32 v61, v233, v63, vcc
	s_and_b64 vcc, s[50:51], s[18:19]
	v_cndmask_b32_e32 v62, v233, v64, vcc
	s_and_b64 vcc, s[52:53], s[18:19]
	v_cndmask_b32_e32 v63, v233, v65, vcc
	v_max3_f32 v64, v48, v49, v32
	v_max3_f32 v65, v50, v51, v33
	s_nop 0
	v_max3_f32 v64, v64, v34, v35
	v_max3_f32 v65, v65, v54, v55
	s_nop 0
	v_max3_f32 v64, v64, v52, v53
	v_max3_f32 v65, v65, v38, v39
	s_nop 0
	v_max3_f32 v64, v64, v36, v37
	v_max3_f32 v65, v65, v58, v59
	s_nop 0
	v_max3_f32 v64, v64, v56, v57
	v_max3_f32 v65, v65, v42, v43
	s_nop 0
	v_max3_f32 v64, v64, v40, v41
	v_max3_f32 v65, v65, v62, v63
	s_nop 0
	v_max3_f32 v64, v64, v60, v61
	v_max3_f32 v65, v65, v46, v47
	s_nop 0
	v_max3_f32 v64, v64, v44, v45
	s_nop 0
	v_max3_f32 v64, v64, v65, v65
	ds_bpermute_b32 v65, v172, v64
	s_waitcnt lgkmcnt(0)
	v_max3_f32 v64, v64, v65, v64
	s_nop 0
	v_cmp_lt_f32_e32 vcc, s78, v64
	s_cbranch_vccz .LBB0_512
	v_max_f32_e32 v64, v64, v64
	v_max_f32_e32 v64, 0, v64
	v_exp_f32_e64 v66, -v64
	v_add_f32_e32 v161, v161, v64
	v_pk_add_f32 v[48:49], v[48:49], v[64:65] op_sel_hi:[1,0] neg_lo:[0,1] neg_hi:[0,1]
	v_pk_add_f32 v[32:33], v[32:33], v[64:65] op_sel_hi:[1,0] neg_lo:[0,1] neg_hi:[0,1]
	v_mul_f32_e32 v132, v132, v66
	v_pk_add_f32 v[50:51], v[50:51], v[64:65] op_sel_hi:[1,0] neg_lo:[0,1] neg_hi:[0,1]
	v_pk_add_f32 v[34:35], v[34:35], v[64:65] op_sel_hi:[1,0] neg_lo:[0,1] neg_hi:[0,1]
	v_pk_add_f32 v[52:53], v[52:53], v[64:65] op_sel_hi:[1,0] neg_lo:[0,1] neg_hi:[0,1]
	v_pk_add_f32 v[36:37], v[36:37], v[64:65] op_sel_hi:[1,0] neg_lo:[0,1] neg_hi:[0,1]
	v_pk_add_f32 v[54:55], v[54:55], v[64:65] op_sel_hi:[1,0] neg_lo:[0,1] neg_hi:[0,1]
	v_pk_add_f32 v[38:39], v[38:39], v[64:65] op_sel_hi:[1,0] neg_lo:[0,1] neg_hi:[0,1]
	v_pk_add_f32 v[56:57], v[56:57], v[64:65] op_sel_hi:[1,0] neg_lo:[0,1] neg_hi:[0,1]
	v_pk_add_f32 v[40:41], v[40:41], v[64:65] op_sel_hi:[1,0] neg_lo:[0,1] neg_hi:[0,1]
	v_pk_add_f32 v[58:59], v[58:59], v[64:65] op_sel_hi:[1,0] neg_lo:[0,1] neg_hi:[0,1]
	v_pk_add_f32 v[42:43], v[42:43], v[64:65] op_sel_hi:[1,0] neg_lo:[0,1] neg_hi:[0,1]
	v_pk_add_f32 v[60:61], v[60:61], v[64:65] op_sel_hi:[1,0] neg_lo:[0,1] neg_hi:[0,1]
	v_pk_add_f32 v[44:45], v[44:45], v[64:65] op_sel_hi:[1,0] neg_lo:[0,1] neg_hi:[0,1]
	v_pk_add_f32 v[62:63], v[62:63], v[64:65] op_sel_hi:[1,0] neg_lo:[0,1] neg_hi:[0,1]
	v_pk_add_f32 v[46:47], v[46:47], v[64:65] op_sel_hi:[1,0] neg_lo:[0,1] neg_hi:[0,1]
	v_pk_mul_f32 v[30:31], v[30:31], v[66:67] op_sel_hi:[1,0]
	v_pk_mul_f32 v[28:29], v[28:29], v[66:67] op_sel_hi:[1,0]
	v_pk_mul_f32 v[26:27], v[26:27], v[66:67] op_sel_hi:[1,0]
	v_pk_mul_f32 v[24:25], v[24:25], v[66:67] op_sel_hi:[1,0]
	v_pk_mul_f32 v[22:23], v[22:23], v[66:67] op_sel_hi:[1,0]
	v_pk_mul_f32 v[20:21], v[20:21], v[66:67] op_sel_hi:[1,0]
	v_pk_mul_f32 v[18:19], v[18:19], v[66:67] op_sel_hi:[1,0]
	v_pk_mul_f32 v[16:17], v[16:17], v[66:67] op_sel_hi:[1,0]
	v_pk_mul_f32 v[14:15], v[14:15], v[66:67] op_sel_hi:[1,0]
	v_pk_mul_f32 v[12:13], v[12:13], v[66:67] op_sel_hi:[1,0]
	v_pk_mul_f32 v[10:11], v[10:11], v[66:67] op_sel_hi:[1,0]
	v_pk_mul_f32 v[8:9], v[8:9], v[66:67] op_sel_hi:[1,0]
	v_pk_mul_f32 v[6:7], v[6:7], v[66:67] op_sel_hi:[1,0]
	v_pk_mul_f32 v[4:5], v[4:5], v[66:67] op_sel_hi:[1,0]
	v_pk_mul_f32 v[2:3], v[2:3], v[66:67] op_sel_hi:[1,0]
	v_pk_mul_f32 v[0:1], v[0:1], v[66:67] op_sel_hi:[1,0]
